# conversion rebalance: +496 items from P0 to L0 up-proj idle WGs (7 per wave) on top of v22
# baseline (speedup 1.0000x reference)
.LBB0_6:
	s_or_b64 exec, exec, s[6:7]
	s_mov_b64 s[22:23], s[0:1]
	v_mov_b32_e32 v3, v224
	s_load_dwordx2 s[18:19], s[22:23], 0xa0
	s_lshl_b32 s33, s24, 3
	v_readfirstlane_b32 s3, v3
	s_ashr_i32 s42, s3, 6
	s_lshl_b32 s3, s77, 3
	s_add_i32 s20, s42, s3
	s_cmpk_lg_i32 s24, 0x100
	v_writelane_b32 v252, s3, 0
	s_cselect_b64 s[6:7], -1, 0
	s_cmpk_eq_i32 s24, 0x100
	s_movk_i32 s3, 0x1d50
	s_cselect_b32 s3, s3, 0x2f00
	v_writelane_b32 v252, s6, 1
	s_cmp_lt_i32 s20, s3
	v_and_b32_e32 v1, 63, v3
	v_writelane_b32 v252, s7, 2
	s_cbranch_scc0 .LBB0_97
	s_mul_hi_i32 s6, s20, 0xae4c415d
	s_add_i32 s6, s6, s20
	s_lshr_b32 s7, s6, 31
	s_ashr_i32 s6, s6, 12
	s_add_i32 s6, s6, s7
	s_mul_i32 s7, s6, 0x1780
	s_sub_i32 s27, s20, s7
	s_waitcnt lgkmcnt(0)
	s_add_u32 s21, s18, 0x100000
	s_addc_u32 s54, s19, 0
	s_mul_i32 s26, s6, 0x1780000
	s_mul_hi_i32 s7, s6, 0x1780000
	s_add_u32 s36, s21, s26
	s_addc_u32 s37, s54, s7
	s_lshl_b32 s34, s6, 10
	s_load_dwordx4 s[8:11], s[22:23], 0x8
	s_load_dwordx4 s[12:15], s[22:23], 0x60
	s_load_dwordx2 s[28:29], s[22:23], 0x70
	s_load_dwordx2 s[30:31], s[22:23], 0x88
	s_ashr_i32 s35, s34, 31
	s_lshl_b64 s[34:35], s[34:35], 2
	s_waitcnt lgkmcnt(0)
	s_add_u32 s38, s8, s34
	s_addc_u32 s39, s9, s35
	s_mul_i32 s26, s6, 0xa00000
	s_mul_hi_i32 s7, s6, 0xa00000
	s_add_u32 s43, s10, s26
	s_addc_u32 s44, s11, s7
	s_cmpk_lt_i32 s27, 0x500
	s_mov_b32 s26, 1
	s_cbranch_scc1 .LBB0_11
	s_ashr_i32 s7, s6, 31
	s_lshl_b64 s[38:39], s[6:7], 22
	s_add_u32 s43, s12, s38
	s_addc_u32 s44, s13, s39
	s_add_u32 s40, s36, 0x500000
	s_addc_u32 s41, s37, 0
	s_cmpk_lt_u32 s27, 0x700
	s_cbranch_scc1 .LBB0_12
	s_cmpk_lt_u32 s27, 0x1200
	s_mul_i32 s26, s6, 0xb00000
	s_cselect_b64 s[40:41], -1, 0
	s_mul_hi_i32 s7, s6, 0xb00000
	s_add_u32 s26, s30, s26
	s_addc_u32 s38, s31, s7
	s_mul_hi_i32 s7, s6, 0x1600000
	s_mul_i32 s6, s6, 0x1600000
	s_add_u32 s39, s28, s6
	s_addc_u32 s43, s29, s7
	s_add_u32 s34, s14, s34
	s_addc_u32 s35, s15, s35
	s_and_b64 s[6:7], s[40:41], exec
	s_mov_b32 s6, 0x700000
	s_cselect_b32 s6, s6, 0x1200000
	s_cselect_b32 s44, s43, s38
	s_cselect_b32 s43, s39, s26
	s_cselect_b32 s39, s35, 0
	s_cselect_b32 s38, s34, 0
	s_add_u32 s36, s36, s6
	s_addc_u32 s37, s37, 0
	s_and_b64 s[6:7], s[40:41], exec
	s_movk_i32 s7, 0xf900
	s_movk_i32 s26, 0x400
	s_movk_i32 s6, 0x1600
	s_cselect_b32 s7, s7, 0xffffee00
	s_cselect_b32 s55, s26, 0xb00
	s_cselect_b32 s6, s6, 0x400
	s_cselect_b32 s26, 2, 0
	s_add_i32 s27, s27, s7
	s_branch .LBB0_13

.LBB0_295:
	s_cmpk_lt_i32 s64, 0x80
	s_cselect_b64 s[8:9], -1, 0
	s_and_b64 s[8:9], s[40:41], s[8:9]
	s_andn2_b64 vcc, exec, s[8:9]
	s_cbranch_vccnz .LBB0_391
	v_mov_b32_e32 v1, v224
	s_nop 0
	v_readfirstlane_b32 s8, v1
	s_ashr_i32 s54, s8, 6
	s_lshl_b32 s8, s64, 3
	s_add_i32 s8, s8, s54
	s_add_i32 s67, s8, 0x1d50
	s_cmpk_gt_i32 s67, 0x214f
	s_cbranch_scc1 .LBB0_391
	s_mul_hi_i32 s8, s67, 0xae4c415d
	s_add_i32 s8, s8, s67
	s_load_dwordx4 s[12:15], s[36:37], 0x8
	s_load_dwordx4 s[16:19], s[36:37], 0x60
	s_load_dwordx2 s[10:11], s[36:37], 0x70
	s_load_dwordx2 s[42:43], s[36:37], 0x88
	s_lshr_b32 s9, s8, 31
	s_ashr_i32 s8, s8, 12
	s_add_i32 s50, s8, s9
	s_mul_i32 s8, s50, 0x1780
	s_sub_i32 s55, s67, s8
	s_ashr_i32 s51, s50, 31
	s_mul_i32 s9, s50, 0x1780000
	s_mul_hi_i32 s8, s50, 0x1780000
	s_add_u32 s46, s65, s9
	s_addc_u32 s47, s66, s8
	s_cmpk_gt_i32 s55, 0x4ff
	s_cbranch_scc0 .LBB0_302
	s_cmpk_gt_u32 s55, 0x6ff
	s_cbranch_scc0 .LBB0_303
	s_cmpk_gt_u32 s55, 0x11ff
	s_cbranch_scc0 .LBB0_708
	s_add_i32 s56, s55, 0xffffee00
	s_mul_i32 s8, s50, 0xb00000
	s_mul_hi_i32 s9, s50, 0xb00000
	s_waitcnt lgkmcnt(0)
	s_add_u32 s8, s42, s8
	s_addc_u32 s9, s43, s9
	s_add_u32 s44, s46, 0x1200000
	s_addc_u32 s45, s47, 0
	s_mov_b64 s[52:53], 0
	s_cbranch_execz .LBB0_709
	s_movk_i32 s68, 0xb00
	s_movk_i32 s27, 0x400
	s_mov_b32 s26, 0
	s_mov_b64 s[48:49], 0
	s_andn2_b64 vcc, exec, s[52:53]
	s_cbranch_vccz .LBB0_304
	s_branch .LBB0_305

.LBB0_309:
	s_add_i32 s8, s27, 0xfffffc00
	s_addk_i32 s67, 0x400
	s_cmpk_lt_i32 s8, 0x1d50
	s_cselect_b64 s[56:57], -1, 0
	s_cmpk_gt_i32 s8, 0x1d4f
	s_mov_b32 s58, s46
	s_mov_b32 s62, s50
	s_cbranch_scc1 .LBB0_322
	s_mul_hi_i32 s8, s27, 0xae4c415d
	s_add_i32 s8, s8, s27
	s_lshr_b32 s9, s8, 31
	s_ashr_i32 s8, s8, 12
	s_add_i32 s60, s8, s9
	s_mul_i32 s8, s60, 0xffffe880
	s_add_i32 s70, s27, s8
	s_ashr_i32 s61, s60, 31
	s_mul_i32 s9, s60, 0x1780000
	s_mul_hi_i32 s8, s60, 0x1780000
	s_add_u32 s58, s65, s9
	s_addc_u32 s59, s66, s8
	s_cmpk_gt_i32 s70, 0x4ff
	s_mov_b64 s[62:63], -1
	s_cbranch_scc0 .LBB0_319
	s_mul_i32 s8, s60, 0x1780
	s_sub_i32 s80, s67, s8
	s_cmpk_gt_u32 s70, 0x6ff
	s_cbranch_scc0 .LBB0_316
	s_cmpk_gt_u32 s70, 0x11ff
	s_mov_b64 s[54:55], -1
	s_cbranch_scc0 .LBB0_314
	s_add_i32 s79, s80, 0xffffee00
	s_mul_i32 s8, s60, 0xb00000
	s_mul_hi_i32 s9, s60, 0xb00000
	s_waitcnt lgkmcnt(0)
	s_add_u32 s8, s42, s8
	s_addc_u32 s9, s43, s9
	s_add_u32 s52, s58, 0x1200000
	s_addc_u32 s53, s59, 0
	s_mov_b64 s[54:55], 0

.LBB0_892:
	s_mov_b32 s10, s2
	s_mov_b32 s11, s24
	s_cmpk_eq_i32 s11, 0x100
	s_cselect_b64 s[12:13], -1, 0
	s_cmpk_gt_i32 s10, 0xc1
	s_cselect_b64 s[14:15], -1, 0
	s_and_b64 s[12:13], s[12:13], s[14:15]
	s_andn2_b64 vcc, exec, s[12:13]
	s_cbranch_vccnz .LBB0_988
	v_mov_b32_e32 v1, v224
	s_lshl_b32 s10, s10, 3
	v_readfirstlane_b32 s11, v1
	s_ashr_i32 s50, s11, 6
	s_add_i32 s10, s10, s50
	s_add_i32 s60, s10, 0x1b40
	s_cmpk_gt_i32 s60, 0x2eff
	s_cbranch_scc1 .LBB0_988
	s_mul_hi_i32 s10, s60, 0xae4c415d
	s_add_i32 s10, s10, s60
	s_lshr_b32 s11, s10, 31
	s_ashr_i32 s10, s10, 12
	s_add_i32 s46, s10, s11
	s_load_dwordx4 s[12:15], s[38:39], 0x8
	s_load_dwordx4 s[16:19], s[38:39], 0x60
	s_load_dwordx2 s[40:41], s[38:39], 0x70
	s_nop 0
	s_load_dwordx2 s[38:39], s[38:39], 0x88
	s_mul_i32 s10, s46, 0x1780
	s_sub_i32 s51, s60, s10
	s_add_u32 s61, s36, 0x100000
	s_addc_u32 s62, s37, 0
	s_ashr_i32 s47, s46, 31
	s_mul_i32 s11, s46, 0x1780000
	s_mul_hi_i32 s10, s46, 0x1780000
	s_add_u32 s42, s61, s11
	s_addc_u32 s43, s62, s10
	s_cmpk_gt_i32 s51, 0x4ff
	s_cbranch_scc0 .LBB0_899
	s_cmpk_gt_u32 s51, 0x6ff
	s_cbranch_scc0 .LBB0_900
	s_cmpk_gt_u32 s51, 0x11ff
	s_cbranch_scc0 .LBB0_1578
	s_add_i32 s52, s51, 0xffffee00
	s_mul_i32 s10, s46, 0xb00000
	s_mul_hi_i32 s11, s46, 0xb00000
	s_waitcnt lgkmcnt(0)
	s_add_u32 s10, s38, s10
	s_addc_u32 s11, s39, s11
	s_add_u32 s36, s42, 0x1200000
	s_addc_u32 s37, s43, 0
	s_mov_b64 s[48:49], 0
	s_cbranch_execz .LBB0_1579
	s_movk_i32 s63, 0xb00
	s_movk_i32 s27, 0x400
	s_mov_b32 s26, 0
	s_mov_b64 s[44:45], 0
	s_andn2_b64 vcc, exec, s[48:49]
	s_cbranch_vccz .LBB0_901
	s_branch .LBB0_902
